# GEMM K-loop on v_mfma_f32_16x16x32_bf16 tiles (same bf16 operands and f32 accumulation), accumulators transposed to the 32x32 layout through LDS before the unchanged epilogues
# speedup vs baseline: 1.0387x; 1.0387x over previous
.LBB0_485:
	s_and_b32 s76, s92, 63
	s_mulk_i32 s76, 0xc0
	v_add_u32_e32 v8, s76, v136
	v_ashrrev_i32_e32 v9, 31, v8
	s_lshl_b32 s77, s84, 8
	s_waitcnt vmcnt(3)
	v_mul_lo_u32 v10, s20, v9
	v_mul_lo_u32 v11, s21, v8
	v_mad_u64_u32 v[8:9], s[86:87], s20, v8, 0
	v_add3_u32 v9, v9, v10, v11
	v_add_u32_e32 v10, s77, v136
	v_mad_u64_u32 v[12:13], s[86:87], v10, s28, 0
	v_ashrrev_i32_e32 v11, 31, v10
	s_waitcnt vmcnt(2)
	v_mov_b32_e32 v14, v13
	v_mad_u64_u32 v[14:15], s[86:87], v11, s28, v[14:15]
	v_lshl_add_u64 v[8:9], v[8:9], 1, s[56:57]
	v_mov_b32_e32 v13, v14
	v_readfirstlane_b32 s84, v137
	v_add_u32_e32 v14, 0x2000, v137
	v_lshl_add_u64 v[8:9], v[8:9], 0, v[0:1]
	s_mov_b32 m0, s84
	s_lshl_b64 s[86:87], s[20:21], 7
	v_readfirstlane_b32 s84, v14
	v_add_u32_e32 v14, 0x4000, v137
	global_load_lds_dwordx4 v[8:9], off
	v_lshl_add_u64 v[8:9], v[8:9], 0, s[86:87]
	s_mov_b32 m0, s84
	v_readfirstlane_b32 s84, v14
	v_lshl_add_u64 v[12:13], v[12:13], 1, s[2:3]
	global_load_lds_dwordx4 v[8:9], off
	v_lshl_add_u64 v[8:9], v[8:9], 0, s[86:87]
	s_mov_b32 m0, s84
	s_lshl_b64 s[86:87], s[28:29], 7
	global_load_lds_dwordx4 v[8:9], off
	v_lshl_add_u64 v[8:9], v[12:13], 0, v[0:1]
	v_add_u32_e32 v12, 0x6000, v137
	s_and_b32 s34, s79, 63
	v_readfirstlane_b32 s84, v12
	v_add_u32_e32 v12, 0x8000, v137
	s_mov_b32 m0, s84
	v_readfirstlane_b32 s84, v12
	v_add_u32_e32 v12, 0xa000, v137
	global_load_lds_dwordx4 v[8:9], off
	v_lshl_add_u64 v[8:9], v[8:9], 0, s[86:87]
	s_mov_b32 m0, s84
	v_readfirstlane_b32 s84, v12
	v_add_u32_e32 v12, 0xc000, v137
	global_load_lds_dwordx4 v[8:9], off
	v_lshl_add_u64 v[8:9], v[8:9], 0, s[86:87]
	s_mov_b32 m0, s84
	v_readfirstlane_b32 s84, v12
	global_load_lds_dwordx4 v[8:9], off
	v_lshl_add_u64 v[8:9], v[8:9], 0, s[86:87]
	s_mov_b32 m0, s84
	s_mulk_i32 s34, 0xc0
	global_load_lds_dwordx4 v[8:9], off
	s_mov_b64 s[4:5], 0x80
	v_lshl_add_u64 v[8:9], s[56:57], 0, v[98:99]
	v_add_u32_e32 v2, s34, v136
	v_lshl_add_u64 v[8:9], v[8:9], 0, s[4:5]
	s_lshl_b32 s86, s20, 1
	v_ashrrev_i32_e32 v3, 31, v2
	v_mad_u64_u32 v[100:101], s[56:57], s86, v2, v[8:9]
	v_lshlrev_b64 v[4:5], 1, v[2:3]
	s_mov_b64 s[6:7], 0x100
	s_lshr_b64 s[56:57], s[20:21], 31
	v_lshl_add_u64 v[6:7], v[4:5], 0, s[6:7]
	v_mul_lo_u32 v2, s56, v2
	v_mul_lo_u32 v3, s86, v3
	v_lshl_add_u64 v[4:5], v[4:5], 0, s[4:5]
	v_add3_u32 v101, v2, v101, v3
	v_mul_lo_u32 v2, s20, v7
	v_mul_lo_u32 v3, s21, v6
	v_mad_u64_u32 v[102:103], s[56:57], s20, v6, v[8:9]
	v_add3_u32 v103, v3, v103, v2
	v_mul_lo_u32 v2, s20, v5
	v_mul_lo_u32 v3, s21, v4
	v_mad_u64_u32 v[104:105], s[20:21], s20, v4, v[8:9]
	v_add3_u32 v105, v3, v105, v2
	v_lshl_add_u64 v[2:3], s[2:3], 0, v[98:99]
	v_lshl_add_u64 v[2:3], v[2:3], 0, s[4:5]
	v_lshlrev_b64 v[4:5], 1, v[10:11]
	v_mad_u64_u32 v[106:107], s[2:3], v4, s28, v[2:3]
	v_alignbit_b32 v7, v11, v10, 31
	v_mov_b32_e32 v6, v107
	v_mad_u64_u32 v[6:7], s[2:3], v7, s28, v[6:7]
	v_mov_b32_e32 v107, v6
	v_lshl_add_u64 v[6:7], v[4:5], 0, s[6:7]
	v_mad_u64_u32 v[108:109], s[2:3], v6, s28, v[2:3]
	v_mov_b32_e32 v6, v109
	v_mad_u64_u32 v[6:7], s[2:3], v7, s28, v[6:7]
	s_mov_b64 s[2:3], 0x180
	v_mov_b32_e32 v109, v6
	v_lshl_add_u64 v[6:7], v[4:5], 0, s[2:3]
	v_lshl_add_u64 v[4:5], v[4:5], 0, s[4:5]
	v_mad_u64_u32 v[110:111], s[2:3], v6, s28, v[2:3]
	v_mad_u64_u32 v[112:113], s[2:3], v4, s28, v[2:3]
	v_mov_b32_e32 v6, v111
	v_mov_b32_e32 v2, v113
	s_waitcnt vmcnt(0)
	v_mad_u64_u32 v[6:7], s[2:3], v7, s28, v[6:7]
	v_mad_u64_u32 v[2:3], s[2:3], v5, s28, v[2:3]
	v_mov_b32_e32 v113, v2
	s_lshl_b64 s[2:3], s[28:29], 1
	v_mov_b32_e32 v2, 0
	s_mov_b32 s34, 1
	s_lshr_b32 s84, s28, 6
	v_mov_b32_e32 v111, v6
	s_and_b32 s20, s2, 0xffffff80
	s_mov_b64 s[2:3], 0
	v_mov_b32_e32 v3, v2
	v_mov_b32_e32 v4, v2
	v_mov_b32_e32 v5, v2
	v_mov_b32_e32 v6, v2
	v_mov_b32_e32 v7, v2
	v_mov_b32_e32 v8, v2
	v_mov_b32_e32 v9, v2
	v_mov_b32_e32 v10, v2
	v_mov_b32_e32 v11, v2
	v_mov_b32_e32 v12, v2
	v_mov_b32_e32 v13, v2
	v_mov_b32_e32 v14, v2
	v_mov_b32_e32 v15, v2
	v_mov_b32_e32 v16, v2
	v_mov_b32_e32 v17, v2
	s_waitcnt vmcnt(0)
	v_mov_b32_e32 v18, v2
	v_mov_b32_e32 v19, v2
	v_mov_b32_e32 v20, v2
	v_mov_b32_e32 v21, v2
	v_mov_b32_e32 v22, v2
	v_mov_b32_e32 v23, v2
	v_mov_b32_e32 v24, v2
	v_mov_b32_e32 v25, v2
	v_mov_b32_e32 v26, v2
	v_mov_b32_e32 v27, v2
	v_mov_b32_e32 v28, v2
	v_mov_b32_e32 v29, v2
	v_mov_b32_e32 v30, v2
	v_mov_b32_e32 v31, v2
	v_mov_b32_e32 v32, v2
	v_mov_b32_e32 v33, v2
	v_mov_b32_e32 v34, v2
	v_mov_b32_e32 v35, v2
	v_mov_b32_e32 v36, v2
	v_mov_b32_e32 v37, v2
	v_mov_b32_e32 v38, v2
	v_mov_b32_e32 v39, v2
	v_mov_b32_e32 v40, v2
	v_mov_b32_e32 v41, v2
	v_mov_b32_e32 v42, v2
	v_mov_b32_e32 v43, v2
	v_mov_b32_e32 v44, v2
	v_mov_b32_e32 v45, v2
	v_mov_b32_e32 v46, v2
	v_mov_b32_e32 v47, v2
	v_mov_b32_e32 v48, v2
	v_mov_b32_e32 v49, v2
	v_mov_b32_e32 v50, v2
	v_mov_b32_e32 v51, v2
	v_mov_b32_e32 v52, v2
	v_mov_b32_e32 v53, v2
	v_mov_b32_e32 v54, v2
	v_mov_b32_e32 v55, v2
	v_mov_b32_e32 v56, v2
	v_mov_b32_e32 v57, v2
	v_mov_b32_e32 v58, v2
	v_mov_b32_e32 v59, v2
	v_mov_b32_e32 v60, v2
	v_mov_b32_e32 v61, v2
	v_mov_b32_e32 v62, v2
	v_mov_b32_e32 v63, v2
	v_mov_b32_e32 v64, v2
	v_mov_b32_e32 v65, v2
	v_mov_b32_e32 v66, v2
	v_mov_b32_e32 v67, v2
	v_mov_b32_e32 v68, v2
	v_mov_b32_e32 v69, v2
	v_mov_b32_e32 v70, v2
	v_mov_b32_e32 v71, v2
	v_mov_b32_e32 v72, v2
	v_mov_b32_e32 v73, v2
	v_mov_b32_e32 v74, v2
	v_mov_b32_e32 v75, v2
	v_mov_b32_e32 v76, v2
	v_mov_b32_e32 v77, v2
	v_mov_b32_e32 v78, v2
	v_mov_b32_e32 v79, v2
	v_mov_b32_e32 v80, v2
	v_mov_b32_e32 v81, v2
	v_mov_b32_e32 v82, v2
	v_mov_b32_e32 v83, v2
	v_mov_b32_e32 v84, v2
	v_mov_b32_e32 v85, v2
	v_mov_b32_e32 v86, v2
	v_mov_b32_e32 v87, v2
	v_mov_b32_e32 v88, v2
	v_mov_b32_e32 v89, v2
	v_mov_b32_e32 v90, v2
	v_mov_b32_e32 v91, v2
	v_mov_b32_e32 v92, v2
	v_mov_b32_e32 v93, v2
	v_mov_b32_e32 v94, v2
	v_mov_b32_e32 v95, v2
	v_mov_b32_e32 v96, v2
	v_mov_b32_e32 v97, v2
	s_waitcnt lgkmcnt(0)
	s_barrier
	v_readfirstlane_b32 s4, v137
	v_and_b32_e32 v172, 63, v203
	v_lshrrev_b32_e32 v173, 6, v203
	v_and_b32_e32 v174, 15, v172
	v_lshrrev_b32_e32 v175, 4, v172
	v_bfe_u32 v176, v172, 1, 3
	v_xor_b32_e32 v177, v175, v176
	v_lshlrev_b32_e32 v177, 4, v177
	v_or_b32_e32 v175, 4, v175
	v_xor_b32_e32 v175, v175, v176
	v_lshlrev_b32_e32 v175, 4, v175
	v_lshrrev_b32_e32 v176, 2, v173
	v_and_b32_e32 v173, 3, v173
	v_mul_u32_u24_e32 v176, 0x60, v176
	v_add_u32_e32 v176, v176, v174
	v_lshlrev_b32_e32 v176, 7, v176
	v_lshl_add_u32 v173, v173, 6, v174
	v_lshlrev_b32_e32 v173, 7, v173
	v_add_u32_e32 v173, 0x6020, v173
	v_add_u32_e32 v176, 32, v176
	v_add_u32_e32 v204, v176, v177
	v_add_u32_e32 v205, v176, v175
	v_add_u32_e32 v206, v173, v177
	v_add_u32_e32 v207, v173, v175
	s_cmp_ge_u32 s34, s84
	s_cbranch_scc1 .Lgk_last
.Lgk_main:
	s_bitcmp1_b32 s34, 0
	s_cselect_b32 s21, 0, 0xec00
	s_cselect_b32 s5, 0xec00, 0
	s_add_i32 s5, s5, s4
	s_mov_b32 m0, s5
	v_lshl_add_u64 v[176:177], v[100:101], 0, s[2:3]
	global_load_lds_dwordx4 v[176:177], off
	s_add_i32 m0, s5, 0x2000
	v_lshl_add_u64 v[176:177], v[104:105], 0, s[2:3]
	global_load_lds_dwordx4 v[176:177], off
	s_add_i32 m0, s5, 0x4000
	v_lshl_add_u64 v[176:177], v[102:103], 0, s[2:3]
	global_load_lds_dwordx4 v[176:177], off
	s_add_i32 m0, s5, 0x6000
	v_lshl_add_u64 v[176:177], v[106:107], 0, s[2:3]
	global_load_lds_dwordx4 v[176:177], off
	s_add_i32 m0, s5, 0x8000
	v_lshl_add_u64 v[176:177], v[112:113], 0, s[2:3]
	global_load_lds_dwordx4 v[176:177], off
	s_add_i32 m0, s5, 0xa000
	v_lshl_add_u64 v[176:177], v[108:109], 0, s[2:3]
	global_load_lds_dwordx4 v[176:177], off
	s_add_i32 m0, s5, 0xc000
	v_lshl_add_u64 v[176:177], v[110:111], 0, s[2:3]
	global_load_lds_dwordx4 v[176:177], off
	v_add_u32_e32 v172, s21, v204
	v_add_u32_e32 v173, s21, v206
	v_add_u32_e32 v174, s21, v205
	v_add_u32_e32 v175, s21, v207
	ds_read_b128 v[208:211], v173
	ds_read_b128 v[212:215], v173 offset:2048
	ds_read_b128 v[216:219], v173 offset:4096
	ds_read_b128 v[220:223], v173 offset:6144
	ds_read_b128 v[148:151], v172
	ds_read_b128 v[152:155], v172 offset:2048
	ds_read_b128 v[156:159], v172 offset:4096
	ds_read_b128 v[160:163], v172 offset:6144
	ds_read_b128 v[164:167], v172 offset:8192
	ds_read_b128 v[168:171], v172 offset:10240
	s_waitcnt lgkmcnt(5)
	v_mfma_f32_16x16x32_bf16 v[82:85], v[148:151], v[208:211], v[82:85]
	v_mfma_f32_16x16x32_bf16 v[86:89], v[148:151], v[212:215], v[86:89]
	v_mfma_f32_16x16x32_bf16 v[66:69], v[148:151], v[216:219], v[66:69]
	v_mfma_f32_16x16x32_bf16 v[70:73], v[148:151], v[220:223], v[70:73]
	ds_read_b128 v[148:151], v174
	ds_read_b128 v[224:227], v175
	ds_read_b128 v[228:231], v175 offset:2048
	ds_read_b128 v[232:235], v175 offset:4096
	ds_read_b128 v[236:239], v175 offset:6144
	s_waitcnt lgkmcnt(9)
	v_mfma_f32_16x16x32_bf16 v[90:93], v[152:155], v[208:211], v[90:93]
	v_mfma_f32_16x16x32_bf16 v[94:97], v[152:155], v[212:215], v[94:97]
	v_mfma_f32_16x16x32_bf16 v[74:77], v[152:155], v[216:219], v[74:77]
	v_mfma_f32_16x16x32_bf16 v[78:81], v[152:155], v[220:223], v[78:81]
	ds_read_b128 v[152:155], v174 offset:2048
	s_waitcnt lgkmcnt(9)
	v_mfma_f32_16x16x32_bf16 v[50:53], v[156:159], v[208:211], v[50:53]
	v_mfma_f32_16x16x32_bf16 v[54:57], v[156:159], v[212:215], v[54:57]
	v_mfma_f32_16x16x32_bf16 v[34:37], v[156:159], v[216:219], v[34:37]
	v_mfma_f32_16x16x32_bf16 v[38:41], v[156:159], v[220:223], v[38:41]
	ds_read_b128 v[156:159], v174 offset:4096
	s_waitcnt lgkmcnt(9)
	v_mfma_f32_16x16x32_bf16 v[58:61], v[160:163], v[208:211], v[58:61]
	v_mfma_f32_16x16x32_bf16 v[62:65], v[160:163], v[212:215], v[62:65]
	v_mfma_f32_16x16x32_bf16 v[42:45], v[160:163], v[216:219], v[42:45]
	v_mfma_f32_16x16x32_bf16 v[46:49], v[160:163], v[220:223], v[46:49]
	ds_read_b128 v[160:163], v174 offset:6144
	s_waitcnt lgkmcnt(9)
	v_mfma_f32_16x16x32_bf16 v[18:21], v[164:167], v[208:211], v[18:21]
	v_mfma_f32_16x16x32_bf16 v[22:25], v[164:167], v[212:215], v[22:25]
	v_mfma_f32_16x16x32_bf16 v[2:5], v[164:167], v[216:219], v[2:5]
	v_mfma_f32_16x16x32_bf16 v[6:9], v[164:167], v[220:223], v[6:9]
	ds_read_b128 v[164:167], v174 offset:8192
	s_waitcnt lgkmcnt(9)
	v_mfma_f32_16x16x32_bf16 v[26:29], v[168:171], v[208:211], v[26:29]
	v_mfma_f32_16x16x32_bf16 v[30:33], v[168:171], v[212:215], v[30:33]
	v_mfma_f32_16x16x32_bf16 v[10:13], v[168:171], v[216:219], v[10:13]
	v_mfma_f32_16x16x32_bf16 v[14:17], v[168:171], v[220:223], v[14:17]
	ds_read_b128 v[168:171], v174 offset:10240
	s_waitcnt lgkmcnt(5)
	v_mfma_f32_16x16x32_bf16 v[82:85], v[148:151], v[224:227], v[82:85]
	v_mfma_f32_16x16x32_bf16 v[86:89], v[148:151], v[228:231], v[86:89]
	v_mfma_f32_16x16x32_bf16 v[66:69], v[148:151], v[232:235], v[66:69]
	v_mfma_f32_16x16x32_bf16 v[70:73], v[148:151], v[236:239], v[70:73]
	s_waitcnt lgkmcnt(4)
	v_mfma_f32_16x16x32_bf16 v[90:93], v[152:155], v[224:227], v[90:93]
	v_mfma_f32_16x16x32_bf16 v[94:97], v[152:155], v[228:231], v[94:97]
	v_mfma_f32_16x16x32_bf16 v[74:77], v[152:155], v[232:235], v[74:77]
	v_mfma_f32_16x16x32_bf16 v[78:81], v[152:155], v[236:239], v[78:81]
	s_waitcnt lgkmcnt(3)
	v_mfma_f32_16x16x32_bf16 v[50:53], v[156:159], v[224:227], v[50:53]
	v_mfma_f32_16x16x32_bf16 v[54:57], v[156:159], v[228:231], v[54:57]
	v_mfma_f32_16x16x32_bf16 v[34:37], v[156:159], v[232:235], v[34:37]
	v_mfma_f32_16x16x32_bf16 v[38:41], v[156:159], v[236:239], v[38:41]
	s_waitcnt lgkmcnt(2)
	v_mfma_f32_16x16x32_bf16 v[58:61], v[160:163], v[224:227], v[58:61]
	v_mfma_f32_16x16x32_bf16 v[62:65], v[160:163], v[228:231], v[62:65]
	v_mfma_f32_16x16x32_bf16 v[42:45], v[160:163], v[232:235], v[42:45]
	v_mfma_f32_16x16x32_bf16 v[46:49], v[160:163], v[236:239], v[46:49]
	s_waitcnt lgkmcnt(1)
	v_mfma_f32_16x16x32_bf16 v[18:21], v[164:167], v[224:227], v[18:21]
	v_mfma_f32_16x16x32_bf16 v[22:25], v[164:167], v[228:231], v[22:25]
	v_mfma_f32_16x16x32_bf16 v[2:5], v[164:167], v[232:235], v[2:5]
	v_mfma_f32_16x16x32_bf16 v[6:9], v[164:167], v[236:239], v[6:9]
	s_waitcnt lgkmcnt(0)
	v_mfma_f32_16x16x32_bf16 v[26:29], v[168:171], v[224:227], v[26:29]
	v_mfma_f32_16x16x32_bf16 v[30:33], v[168:171], v[228:231], v[30:33]
	v_mfma_f32_16x16x32_bf16 v[10:13], v[168:171], v[232:235], v[10:13]
	v_mfma_f32_16x16x32_bf16 v[14:17], v[168:171], v[236:239], v[14:17]
	s_add_i32 s34, s34, 1
	s_add_u32 s2, s2, 0x80
	s_addc_u32 s3, s3, 0
	s_waitcnt vmcnt(0)
	s_barrier
	s_cmp_ge_u32 s34, s84
	s_cbranch_scc0 .Lgk_main
.Lgk_last:
	s_bitcmp1_b32 s34, 0
	s_cselect_b32 s21, 0, 0xec00
	v_add_u32_e32 v172, s21, v204
	v_add_u32_e32 v173, s21, v206
	v_add_u32_e32 v174, s21, v205
	v_add_u32_e32 v175, s21, v207
	ds_read_b128 v[208:211], v173
	ds_read_b128 v[212:215], v173 offset:2048
	ds_read_b128 v[216:219], v173 offset:4096
	ds_read_b128 v[220:223], v173 offset:6144
	ds_read_b128 v[148:151], v172
	ds_read_b128 v[152:155], v172 offset:2048
	ds_read_b128 v[156:159], v172 offset:4096
	ds_read_b128 v[160:163], v172 offset:6144
	ds_read_b128 v[164:167], v172 offset:8192
	ds_read_b128 v[168:171], v172 offset:10240
	s_waitcnt lgkmcnt(5)
	v_mfma_f32_16x16x32_bf16 v[82:85], v[148:151], v[208:211], v[82:85]
	v_mfma_f32_16x16x32_bf16 v[86:89], v[148:151], v[212:215], v[86:89]
	v_mfma_f32_16x16x32_bf16 v[66:69], v[148:151], v[216:219], v[66:69]
	v_mfma_f32_16x16x32_bf16 v[70:73], v[148:151], v[220:223], v[70:73]
	ds_read_b128 v[148:151], v174
	ds_read_b128 v[224:227], v175
	ds_read_b128 v[228:231], v175 offset:2048
	ds_read_b128 v[232:235], v175 offset:4096
	ds_read_b128 v[236:239], v175 offset:6144
	s_waitcnt lgkmcnt(9)
	v_mfma_f32_16x16x32_bf16 v[90:93], v[152:155], v[208:211], v[90:93]
	v_mfma_f32_16x16x32_bf16 v[94:97], v[152:155], v[212:215], v[94:97]
	v_mfma_f32_16x16x32_bf16 v[74:77], v[152:155], v[216:219], v[74:77]
	v_mfma_f32_16x16x32_bf16 v[78:81], v[152:155], v[220:223], v[78:81]
	ds_read_b128 v[152:155], v174 offset:2048
	s_waitcnt lgkmcnt(9)
	v_mfma_f32_16x16x32_bf16 v[50:53], v[156:159], v[208:211], v[50:53]
	v_mfma_f32_16x16x32_bf16 v[54:57], v[156:159], v[212:215], v[54:57]
	v_mfma_f32_16x16x32_bf16 v[34:37], v[156:159], v[216:219], v[34:37]
	v_mfma_f32_16x16x32_bf16 v[38:41], v[156:159], v[220:223], v[38:41]
	ds_read_b128 v[156:159], v174 offset:4096
	s_waitcnt lgkmcnt(9)
	v_mfma_f32_16x16x32_bf16 v[58:61], v[160:163], v[208:211], v[58:61]
	v_mfma_f32_16x16x32_bf16 v[62:65], v[160:163], v[212:215], v[62:65]
	v_mfma_f32_16x16x32_bf16 v[42:45], v[160:163], v[216:219], v[42:45]
	v_mfma_f32_16x16x32_bf16 v[46:49], v[160:163], v[220:223], v[46:49]
	ds_read_b128 v[160:163], v174 offset:6144
	s_waitcnt lgkmcnt(9)
	v_mfma_f32_16x16x32_bf16 v[18:21], v[164:167], v[208:211], v[18:21]
	v_mfma_f32_16x16x32_bf16 v[22:25], v[164:167], v[212:215], v[22:25]
	v_mfma_f32_16x16x32_bf16 v[2:5], v[164:167], v[216:219], v[2:5]
	v_mfma_f32_16x16x32_bf16 v[6:9], v[164:167], v[220:223], v[6:9]
	ds_read_b128 v[164:167], v174 offset:8192
	s_waitcnt lgkmcnt(9)
	v_mfma_f32_16x16x32_bf16 v[26:29], v[168:171], v[208:211], v[26:29]
	v_mfma_f32_16x16x32_bf16 v[30:33], v[168:171], v[212:215], v[30:33]
	v_mfma_f32_16x16x32_bf16 v[10:13], v[168:171], v[216:219], v[10:13]
	v_mfma_f32_16x16x32_bf16 v[14:17], v[168:171], v[220:223], v[14:17]
	ds_read_b128 v[168:171], v174 offset:10240
	s_waitcnt lgkmcnt(5)
	v_mfma_f32_16x16x32_bf16 v[82:85], v[148:151], v[224:227], v[82:85]
	v_mfma_f32_16x16x32_bf16 v[86:89], v[148:151], v[228:231], v[86:89]
	v_mfma_f32_16x16x32_bf16 v[66:69], v[148:151], v[232:235], v[66:69]
	v_mfma_f32_16x16x32_bf16 v[70:73], v[148:151], v[236:239], v[70:73]
	s_waitcnt lgkmcnt(4)
	v_mfma_f32_16x16x32_bf16 v[90:93], v[152:155], v[224:227], v[90:93]
	v_mfma_f32_16x16x32_bf16 v[94:97], v[152:155], v[228:231], v[94:97]
	v_mfma_f32_16x16x32_bf16 v[74:77], v[152:155], v[232:235], v[74:77]
	v_mfma_f32_16x16x32_bf16 v[78:81], v[152:155], v[236:239], v[78:81]
	s_waitcnt lgkmcnt(3)
	v_mfma_f32_16x16x32_bf16 v[50:53], v[156:159], v[224:227], v[50:53]
	v_mfma_f32_16x16x32_bf16 v[54:57], v[156:159], v[228:231], v[54:57]
	v_mfma_f32_16x16x32_bf16 v[34:37], v[156:159], v[232:235], v[34:37]
	v_mfma_f32_16x16x32_bf16 v[38:41], v[156:159], v[236:239], v[38:41]
	s_waitcnt lgkmcnt(2)
	v_mfma_f32_16x16x32_bf16 v[58:61], v[160:163], v[224:227], v[58:61]
	v_mfma_f32_16x16x32_bf16 v[62:65], v[160:163], v[228:231], v[62:65]
	v_mfma_f32_16x16x32_bf16 v[42:45], v[160:163], v[232:235], v[42:45]
	v_mfma_f32_16x16x32_bf16 v[46:49], v[160:163], v[236:239], v[46:49]
	s_waitcnt lgkmcnt(1)
	v_mfma_f32_16x16x32_bf16 v[18:21], v[164:167], v[224:227], v[18:21]
	v_mfma_f32_16x16x32_bf16 v[22:25], v[164:167], v[228:231], v[22:25]
	v_mfma_f32_16x16x32_bf16 v[2:5], v[164:167], v[232:235], v[2:5]
	v_mfma_f32_16x16x32_bf16 v[6:9], v[164:167], v[236:239], v[6:9]
	s_waitcnt lgkmcnt(0)
	v_mfma_f32_16x16x32_bf16 v[26:29], v[168:171], v[224:227], v[26:29]
	v_mfma_f32_16x16x32_bf16 v[30:33], v[168:171], v[228:231], v[30:33]
	v_mfma_f32_16x16x32_bf16 v[10:13], v[168:171], v[232:235], v[10:13]
	v_mfma_f32_16x16x32_bf16 v[14:17], v[168:171], v[236:239], v[14:17]
	s_add_i32 s34, s34, 1
	s_add_u32 s2, s2, 0x80
	s_addc_u32 s3, s3, 0
	s_cmp_eq_u32 s20, s2
	s_waitcnt vmcnt(0)
	s_barrier
	v_and_b32_e32 v172, 63, v203
	v_lshrrev_b32_e32 v173, 6, v203
	v_mul_u32_u24_e32 v173, 0x1200, v173
	v_add_u32_e32 v173, 0xec20, v173
	v_and_b32_e32 v174, 15, v172
	v_lshrrev_b32_e32 v175, 4, v172
	v_mul_u32_u24_e32 v174, 0x90, v174
	v_lshl_add_u32 v174, v175, 4, v174
	v_add_u32_e32 v174, v174, v173
	v_and_b32_e32 v175, 31, v172
	v_lshrrev_b32_e32 v176, 5, v172
	v_mul_u32_u24_e32 v175, 0x90, v175
	v_lshl_add_u32 v175, v176, 4, v175
	v_add_u32_e32 v175, v175, v173
	ds_write_b128 v174, v[82:85]
	ds_write_b128 v174, v[86:89] offset:2304
	ds_write_b128 v174, v[90:93] offset:64
	ds_write_b128 v174, v[94:97] offset:2368
	ds_read_b128 v[82:85], v175
	ds_read_b128 v[86:89], v175 offset:32
	ds_read_b128 v[90:93], v175 offset:64
	ds_read_b128 v[94:97], v175 offset:96
	ds_write_b128 v174, v[66:69]
	ds_write_b128 v174, v[70:73] offset:2304
	ds_write_b128 v174, v[74:77] offset:64
	ds_write_b128 v174, v[78:81] offset:2368
	ds_read_b128 v[66:69], v175
	ds_read_b128 v[70:73], v175 offset:32
	ds_read_b128 v[74:77], v175 offset:64
	ds_read_b128 v[78:81], v175 offset:96
	ds_write_b128 v174, v[50:53]
	ds_write_b128 v174, v[54:57] offset:2304
	ds_write_b128 v174, v[58:61] offset:64
	ds_write_b128 v174, v[62:65] offset:2368
	ds_read_b128 v[50:53], v175
	ds_read_b128 v[54:57], v175 offset:32
	ds_read_b128 v[58:61], v175 offset:64
	ds_read_b128 v[62:65], v175 offset:96
	ds_write_b128 v174, v[34:37]
	ds_write_b128 v174, v[38:41] offset:2304
	ds_write_b128 v174, v[42:45] offset:64
	ds_write_b128 v174, v[46:49] offset:2368
	ds_read_b128 v[34:37], v175
	ds_read_b128 v[38:41], v175 offset:32
	ds_read_b128 v[42:45], v175 offset:64
	ds_read_b128 v[46:49], v175 offset:96
	ds_write_b128 v174, v[18:21]
	ds_write_b128 v174, v[22:25] offset:2304
	ds_write_b128 v174, v[26:29] offset:64
	ds_write_b128 v174, v[30:33] offset:2368
	ds_read_b128 v[18:21], v175
	ds_read_b128 v[22:25], v175 offset:32
	ds_read_b128 v[26:29], v175 offset:64
	ds_read_b128 v[30:33], v175 offset:96
	ds_write_b128 v174, v[2:5]
	ds_write_b128 v174, v[6:9] offset:2304
	ds_write_b128 v174, v[10:13] offset:64
	ds_write_b128 v174, v[14:17] offset:2368
	ds_read_b128 v[2:5], v175
	ds_read_b128 v[6:9], v175 offset:32
	ds_read_b128 v[10:13], v175 offset:64
	ds_read_b128 v[14:17], v175 offset:96
	s_waitcnt lgkmcnt(0)
